# P2-rotary-epilogue-loads-paired-and-prefetched
# speedup vs baseline: 1.0327x; 1.0065x over previous
;     __device__ __forceinline__ void operator()(const f32x4 (&acc)[2][2][4][2], const Unit& u, int wr, int wc, int fr, int fq) const {
;     ...
;             for (int m = 0; m < 4; ++m) {
; #pragma unroll
;                 for (int bj = 0; bj < 2; ++bj) f(row0 + ai * HALF + m * 16, col0 + bj * HALF, acc[ai][bj][m][0], acc[ai][bj][m][1]);
.LBB0_191:
	v_lshl_add_u32 v134, s7, 8, v142
	s_lshl_b32 s48, s6, 8
	v_ashrrev_i32_e32 v135, 31, v134
	s_add_i32 s2, s48, 0xfffff400
	v_lshlrev_b64 v[136:137], 8, v[134:135]
	s_cmpk_lt_u32 s2, 0x600
	s_cselect_b64 s[0:1], -1, 0
	s_cmpk_gt_u32 s2, 0x5ff
	v_lshl_add_u64 v[136:137], v[128:129], 0, v[136:137]
	v_mov_b64_e32 v[224:225], v[136:137]
	s_cbranch_scc1 .LBB0_193
	v_mov_b64_e32 v[226:227], v[224:225]
	global_load_dwordx4 v[192:195], v[226:227], off offset:16
	global_load_dwordx4 v[196:199], v[226:227], off
	s_mov_b64 s[98:99], 0x1000
	v_lshl_add_u64 v[226:227], v[224:225], 0, s[98:99]
	global_load_dwordx4 v[200:203], v[226:227], off offset:16
	global_load_dwordx4 v[204:207], v[226:227], off
	s_cmpk_lt_u32 s48, 0xf00
	s_cselect_b64 vcc, -1, 0
	v_cndmask_b32_e32 v160, 1.0, v151, vcc
	s_waitcnt vmcnt(2)
	v_mov_b32_e32 v152, v192
	v_mov_b32_e32 v153, v193
	v_mov_b32_e32 v154, v194
	v_mov_b32_e32 v155, v195
	v_mov_b32_e32 v156, v196
	v_mov_b32_e32 v157, v197
	v_mov_b32_e32 v158, v198
	v_mov_b32_e32 v159, v199
	v_mov_b32_e32 v162, v153
	v_mov_b32_e32 v163, v155
	v_mov_b32_e32 v164, v157
	v_mov_b32_e32 v165, v159
	v_mov_b32_e32 v157, v158
	v_mov_b32_e32 v153, v154
	v_pk_mul_f32 v[154:155], v[122:123], v[162:163]
	v_pk_mul_f32 v[158:159], v[120:121], v[164:165]
	v_pk_mul_f32 v[162:163], v[126:127], v[162:163]
	v_pk_mul_f32 v[164:165], v[124:125], v[164:165]
	v_pk_fma_f32 v[124:125], v[124:125], v[156:157], v[158:159] neg_lo:[0,0,1] neg_hi:[0,0,1]
	v_pk_fma_f32 v[126:127], v[126:127], v[152:153], v[154:155] neg_lo:[0,0,1] neg_hi:[0,0,1]
	v_pk_fma_f32 v[120:121], v[120:121], v[156:157], v[164:165]
	v_pk_fma_f32 v[122:123], v[122:123], v[152:153], v[162:163]
	v_pk_mul_f32 v[126:127], v[160:161], v[126:127] op_sel_hi:[0,1]
	v_pk_mul_f32 v[124:125], v[160:161], v[124:125] op_sel_hi:[0,1]
	v_pk_mul_f32 v[122:123], v[160:161], v[122:123] op_sel_hi:[0,1]
	v_pk_mul_f32 v[120:121], v[160:161], v[120:121] op_sel_hi:[0,1]
.LBB0_193:
	s_add_i32 s6, s48, 0xfffff480
	v_or_b32_e32 v152, s48, v144
	v_mul_lo_u32 v153, v134, s43
	s_cmpk_lt_u32 s6, 0x600
	v_cvt_pk_bf16_f32 v124, v124, v125
	v_cvt_pk_bf16_f32 v125, v126, v127
	v_cvt_pk_bf16_f32 v126, v120, v121
	v_cvt_pk_bf16_f32 v127, v122, v123
	v_add_lshl_u32 v120, v153, v152, 1
	s_cselect_b64 s[2:3], -1, 0
	s_cmpk_gt_u32 s6, 0x5ff
	global_store_dwordx4 v120, v[124:127], s[16:17]
	s_cbranch_scc1 .LBB0_195
	s_cmpk_lt_u32 s48, 0xf00
	s_cselect_b64 vcc, -1, 0
	v_cndmask_b32_e32 v136, 1.0, v151, vcc
	v_mov_b32_e32 v120, v192
	v_mov_b32_e32 v121, v193
	v_mov_b32_e32 v122, v194
	v_mov_b32_e32 v123, v195
	v_mov_b32_e32 v124, v196
	v_mov_b32_e32 v125, v197
	v_mov_b32_e32 v126, v198
	v_mov_b32_e32 v127, v199
	v_mov_b32_e32 v154, v121
	v_mov_b32_e32 v155, v123
	v_mov_b32_e32 v156, v125
	v_mov_b32_e32 v157, v127
	v_mov_b32_e32 v125, v126
	v_mov_b32_e32 v121, v122
	v_pk_mul_f32 v[122:123], v[114:115], v[154:155]
	v_pk_mul_f32 v[126:127], v[112:113], v[156:157]
	v_pk_mul_f32 v[154:155], v[118:119], v[154:155]
	v_pk_mul_f32 v[156:157], v[116:117], v[156:157]
	v_pk_fma_f32 v[116:117], v[116:117], v[124:125], v[126:127] neg_lo:[0,0,1] neg_hi:[0,0,1]
	v_pk_fma_f32 v[118:119], v[118:119], v[120:121], v[122:123] neg_lo:[0,0,1] neg_hi:[0,0,1]
	v_pk_fma_f32 v[112:113], v[112:113], v[124:125], v[156:157]
	v_pk_fma_f32 v[114:115], v[114:115], v[120:121], v[154:155]
	v_pk_mul_f32 v[118:119], v[136:137], v[118:119] op_sel_hi:[0,1]
	v_pk_mul_f32 v[116:117], v[136:137], v[116:117] op_sel_hi:[0,1]
	v_pk_mul_f32 v[114:115], v[136:137], v[114:115] op_sel_hi:[0,1]
	v_pk_mul_f32 v[112:113], v[136:137], v[112:113] op_sel_hi:[0,1]
.LBB0_195:
	v_or_b32_e32 v120, 0x80, v152
	v_cvt_pk_bf16_f32 v116, v116, v117
	v_cvt_pk_bf16_f32 v117, v118, v119
	v_cvt_pk_bf16_f32 v118, v112, v113
	v_cvt_pk_bf16_f32 v119, v114, v115
	v_add_lshl_u32 v112, v153, v120, 1
	global_store_dwordx4 v112, v[116:119], s[16:17]
	v_or_b32_e32 v112, 16, v134
	v_ashrrev_i32_e32 v113, 31, v112
	v_lshlrev_b64 v[112:113], 8, v[112:113]
	v_cndmask_b32_e64 v114, 0, 1, s[0:1]
	v_cmp_ne_u32_e64 s[6:7], 1, v114
	s_andn2_b64 vcc, exec, s[0:1]
	v_lshl_add_u64 v[112:113], v[128:129], 0, v[112:113]
	s_cbranch_vccnz .LBB0_197
	s_mov_b64 s[98:99], 0x2000
	v_lshl_add_u64 v[226:227], v[224:225], 0, s[98:99]
	global_load_dwordx4 v[208:211], v[226:227], off offset:16
	global_load_dwordx4 v[212:215], v[226:227], off
	s_cmpk_lt_u32 s48, 0xf00
	s_cselect_b64 vcc, -1, 0
	v_cndmask_b32_e32 v118, 1.0, v151, vcc
	s_waitcnt vmcnt(4)
	v_mov_b32_e32 v114, v200
	v_mov_b32_e32 v115, v201
	v_mov_b32_e32 v116, v202
	v_mov_b32_e32 v117, v203
	v_mov_b32_e32 v122, v204
	v_mov_b32_e32 v123, v205
	v_mov_b32_e32 v124, v206
	v_mov_b32_e32 v125, v207
	v_mov_b32_e32 v126, v115
	v_mov_b32_e32 v127, v117
	v_mov_b32_e32 v136, v123
	v_mov_b32_e32 v137, v125
	v_mov_b32_e32 v123, v124
	v_mov_b32_e32 v115, v116
	v_pk_mul_f32 v[116:117], v[106:107], v[126:127]
	v_pk_mul_f32 v[124:125], v[104:105], v[136:137]
	v_pk_mul_f32 v[126:127], v[110:111], v[126:127]
	v_pk_mul_f32 v[136:137], v[108:109], v[136:137]
	v_pk_fma_f32 v[108:109], v[108:109], v[122:123], v[124:125] neg_lo:[0,0,1] neg_hi:[0,0,1]
	v_pk_fma_f32 v[110:111], v[110:111], v[114:115], v[116:117] neg_lo:[0,0,1] neg_hi:[0,0,1]
	v_pk_fma_f32 v[104:105], v[104:105], v[122:123], v[136:137]
	v_pk_fma_f32 v[106:107], v[106:107], v[114:115], v[126:127]
	v_pk_mul_f32 v[110:111], v[118:119], v[110:111] op_sel_hi:[0,1]
	v_pk_mul_f32 v[108:109], v[118:119], v[108:109] op_sel_hi:[0,1]
	v_pk_mul_f32 v[106:107], v[118:119], v[106:107] op_sel_hi:[0,1]
	v_pk_mul_f32 v[104:105], v[118:119], v[104:105] op_sel_hi:[0,1]
;     __device__ __forceinline__ void operator()(const f32x4 (&acc)[2][2][4][2], const Unit& u, int wr, int wc, int fr, int fq) const {
;     ...
;             for (int m = 0; m < 4; ++m) {
; #pragma unroll
;                 for (int bj = 0; bj < 2; ++bj) f(row0 + ai * HALF + m * 16, col0 + bj * HALF, acc[ai][bj][m][0], acc[ai][bj][m][1]);
.LBB0_197:
	v_add_u32_e32 v114, 0x15000, v153
	v_cvt_pk_bf16_f32 v108, v108, v109
	v_cvt_pk_bf16_f32 v109, v110, v111
	v_cvt_pk_bf16_f32 v110, v104, v105
	v_cndmask_b32_e64 v105, 0, 1, s[2:3]
	v_cvt_pk_bf16_f32 v111, v106, v107
	v_add_lshl_u32 v104, v114, v152, 1
	v_cmp_ne_u32_e64 s[8:9], 1, v105
	s_andn2_b64 vcc, exec, s[2:3]
	global_store_dwordx4 v104, v[108:111], s[16:17]
	s_cbranch_vccnz .LBB0_199
	s_cmpk_lt_u32 s48, 0xf00
	s_cselect_b64 vcc, -1, 0
	v_cndmask_b32_e32 v112, 1.0, v151, vcc
	v_mov_b32_e32 v104, v200
	v_mov_b32_e32 v105, v201
	v_mov_b32_e32 v106, v202
	v_mov_b32_e32 v107, v203
	v_mov_b32_e32 v108, v204
	v_mov_b32_e32 v109, v205
	v_mov_b32_e32 v110, v206
	v_mov_b32_e32 v111, v207
	v_mov_b32_e32 v116, v105
	v_mov_b32_e32 v117, v107
	v_mov_b32_e32 v118, v109
	v_mov_b32_e32 v119, v111
	v_mov_b32_e32 v109, v110
	v_mov_b32_e32 v105, v106
	v_pk_mul_f32 v[106:107], v[98:99], v[116:117]
	v_pk_mul_f32 v[110:111], v[96:97], v[118:119]
	v_pk_mul_f32 v[116:117], v[102:103], v[116:117]
	v_pk_mul_f32 v[118:119], v[100:101], v[118:119]
	v_pk_fma_f32 v[100:101], v[100:101], v[108:109], v[110:111] neg_lo:[0,0,1] neg_hi:[0,0,1]
	v_pk_fma_f32 v[102:103], v[102:103], v[104:105], v[106:107] neg_lo:[0,0,1] neg_hi:[0,0,1]
	v_pk_fma_f32 v[96:97], v[96:97], v[108:109], v[118:119]
	v_pk_fma_f32 v[98:99], v[98:99], v[104:105], v[116:117]
	v_pk_mul_f32 v[102:103], v[112:113], v[102:103] op_sel_hi:[0,1]
	v_pk_mul_f32 v[100:101], v[112:113], v[100:101] op_sel_hi:[0,1]
	v_pk_mul_f32 v[98:99], v[112:113], v[98:99] op_sel_hi:[0,1]
	v_pk_mul_f32 v[96:97], v[112:113], v[96:97] op_sel_hi:[0,1]
.LBB0_199:
	v_cvt_pk_bf16_f32 v100, v100, v101
	v_cvt_pk_bf16_f32 v101, v102, v103
	v_cvt_pk_bf16_f32 v102, v96, v97
	v_cvt_pk_bf16_f32 v103, v98, v99
	v_add_lshl_u32 v96, v114, v120, 1
	global_store_dwordx4 v96, v[100:103], s[16:17]
	v_or_b32_e32 v96, 32, v134
	v_ashrrev_i32_e32 v97, 31, v96
	v_lshlrev_b64 v[96:97], 8, v[96:97]
	s_and_b64 vcc, exec, s[6:7]
	v_lshl_add_u64 v[96:97], v[128:129], 0, v[96:97]
	s_cbranch_vccnz .LBB0_201
	s_mov_b64 s[98:99], 0x3000
	v_lshl_add_u64 v[226:227], v[224:225], 0, s[98:99]
	global_load_dwordx4 v[216:219], v[226:227], off offset:16
	global_load_dwordx4 v[220:223], v[226:227], off
	s_cmpk_lt_u32 s48, 0xf00
	s_cselect_b64 vcc, -1, 0
	v_cndmask_b32_e32 v106, 1.0, v151, vcc
	s_waitcnt vmcnt(4)
	v_mov_b32_e32 v98, v208
	v_mov_b32_e32 v99, v209
	v_mov_b32_e32 v100, v210
	v_mov_b32_e32 v101, v211
	v_mov_b32_e32 v102, v212
	v_mov_b32_e32 v103, v213
	v_mov_b32_e32 v104, v214
	v_mov_b32_e32 v105, v215
	v_mov_b32_e32 v108, v99
	v_mov_b32_e32 v109, v101
	v_mov_b32_e32 v110, v103
	v_mov_b32_e32 v111, v105
	v_mov_b32_e32 v103, v104
	v_mov_b32_e32 v99, v100
	v_pk_mul_f32 v[100:101], v[90:91], v[108:109]
	v_pk_mul_f32 v[104:105], v[88:89], v[110:111]
	v_pk_mul_f32 v[108:109], v[94:95], v[108:109]
	v_pk_mul_f32 v[110:111], v[92:93], v[110:111]
	v_pk_fma_f32 v[92:93], v[92:93], v[102:103], v[104:105] neg_lo:[0,0,1] neg_hi:[0,0,1]
	v_pk_fma_f32 v[94:95], v[94:95], v[98:99], v[100:101] neg_lo:[0,0,1] neg_hi:[0,0,1]
	v_pk_fma_f32 v[88:89], v[88:89], v[102:103], v[110:111]
	v_pk_fma_f32 v[90:91], v[90:91], v[98:99], v[108:109]
	v_pk_mul_f32 v[94:95], v[106:107], v[94:95] op_sel_hi:[0,1]
	v_pk_mul_f32 v[92:93], v[106:107], v[92:93] op_sel_hi:[0,1]
	v_pk_mul_f32 v[90:91], v[106:107], v[90:91] op_sel_hi:[0,1]
	v_pk_mul_f32 v[88:89], v[106:107], v[88:89] op_sel_hi:[0,1]
.LBB0_201:
	v_add_u32_e32 v98, 0x15000, v114
	v_cvt_pk_bf16_f32 v92, v92, v93
	v_cvt_pk_bf16_f32 v93, v94, v95
	v_cvt_pk_bf16_f32 v94, v88, v89
	v_cvt_pk_bf16_f32 v95, v90, v91
	v_add_lshl_u32 v88, v98, v152, 1
	s_and_b64 vcc, exec, s[8:9]
	global_store_dwordx4 v88, v[92:95], s[16:17]
	s_cbranch_vccnz .LBB0_203
	s_cmpk_lt_u32 s48, 0xf00
	s_cselect_b64 vcc, -1, 0
	v_cndmask_b32_e32 v96, 1.0, v151, vcc
	v_mov_b32_e32 v88, v208
	v_mov_b32_e32 v89, v209
	v_mov_b32_e32 v90, v210
	v_mov_b32_e32 v91, v211
	v_mov_b32_e32 v92, v212
	v_mov_b32_e32 v93, v213
	v_mov_b32_e32 v94, v214
	v_mov_b32_e32 v95, v215
	v_mov_b32_e32 v100, v89
	v_mov_b32_e32 v101, v91
	v_mov_b32_e32 v102, v93
	v_mov_b32_e32 v103, v95
	v_mov_b32_e32 v93, v94
	v_mov_b32_e32 v89, v90
	v_pk_mul_f32 v[90:91], v[82:83], v[100:101]
	v_pk_mul_f32 v[94:95], v[80:81], v[102:103]
	v_pk_mul_f32 v[100:101], v[86:87], v[100:101]
	v_pk_mul_f32 v[102:103], v[84:85], v[102:103]
	v_pk_fma_f32 v[84:85], v[84:85], v[92:93], v[94:95] neg_lo:[0,0,1] neg_hi:[0,0,1]
	v_pk_fma_f32 v[86:87], v[86:87], v[88:89], v[90:91] neg_lo:[0,0,1] neg_hi:[0,0,1]
	v_pk_fma_f32 v[80:81], v[80:81], v[92:93], v[102:103]
	v_pk_fma_f32 v[82:83], v[82:83], v[88:89], v[100:101]
	v_pk_mul_f32 v[86:87], v[96:97], v[86:87] op_sel_hi:[0,1]
	v_pk_mul_f32 v[84:85], v[96:97], v[84:85] op_sel_hi:[0,1]
	v_pk_mul_f32 v[82:83], v[96:97], v[82:83] op_sel_hi:[0,1]
	v_pk_mul_f32 v[80:81], v[96:97], v[80:81] op_sel_hi:[0,1]
;     __device__ __forceinline__ void operator()(const f32x4 (&acc)[2][2][4][2], const Unit& u, int wr, int wc, int fr, int fq) const {
;     ...
;             for (int m = 0; m < 4; ++m) {
; #pragma unroll
;                 for (int bj = 0; bj < 2; ++bj) f(row0 + ai * HALF + m * 16, col0 + bj * HALF, acc[ai][bj][m][0], acc[ai][bj][m][1]);
.LBB0_203:
	v_cvt_pk_bf16_f32 v84, v84, v85
	v_cvt_pk_bf16_f32 v85, v86, v87
	v_cvt_pk_bf16_f32 v86, v80, v81
	v_cvt_pk_bf16_f32 v87, v82, v83
	v_add_lshl_u32 v80, v98, v120, 1
	global_store_dwordx4 v80, v[84:87], s[16:17]
	v_or_b32_e32 v80, 48, v134
	v_ashrrev_i32_e32 v81, 31, v80
	v_lshlrev_b64 v[80:81], 8, v[80:81]
	s_and_b64 vcc, exec, s[6:7]
	v_lshl_add_u64 v[80:81], v[128:129], 0, v[80:81]
	s_cbranch_vccnz .LBB0_205
	s_mov_b64 s[98:99], 0x8000
	v_lshl_add_u64 v[226:227], v[224:225], 0, s[98:99]
	global_load_dwordx4 v[192:195], v[226:227], off offset:16
	global_load_dwordx4 v[196:199], v[226:227], off
	s_cmpk_lt_u32 s48, 0xf00
	s_cselect_b64 vcc, -1, 0
	v_cndmask_b32_e32 v90, 1.0, v151, vcc
	s_waitcnt vmcnt(4)
	v_mov_b32_e32 v82, v216
	v_mov_b32_e32 v83, v217
	v_mov_b32_e32 v84, v218
	v_mov_b32_e32 v85, v219
	v_mov_b32_e32 v86, v220
	v_mov_b32_e32 v87, v221
	v_mov_b32_e32 v88, v222
	v_mov_b32_e32 v89, v223
	v_mov_b32_e32 v92, v83
	v_mov_b32_e32 v93, v85
	v_mov_b32_e32 v94, v87
	v_mov_b32_e32 v95, v89
	v_mov_b32_e32 v87, v88
	v_mov_b32_e32 v83, v84
	v_pk_mul_f32 v[84:85], v[74:75], v[92:93]
	v_pk_mul_f32 v[88:89], v[72:73], v[94:95]
	v_pk_mul_f32 v[92:93], v[78:79], v[92:93]
	v_pk_mul_f32 v[94:95], v[76:77], v[94:95]
	v_pk_fma_f32 v[76:77], v[76:77], v[86:87], v[88:89] neg_lo:[0,0,1] neg_hi:[0,0,1]
	v_pk_fma_f32 v[78:79], v[78:79], v[82:83], v[84:85] neg_lo:[0,0,1] neg_hi:[0,0,1]
	v_pk_fma_f32 v[72:73], v[72:73], v[86:87], v[94:95]
	v_pk_fma_f32 v[74:75], v[74:75], v[82:83], v[92:93]
	v_pk_mul_f32 v[78:79], v[90:91], v[78:79] op_sel_hi:[0,1]
	v_pk_mul_f32 v[76:77], v[90:91], v[76:77] op_sel_hi:[0,1]
	v_pk_mul_f32 v[74:75], v[90:91], v[74:75] op_sel_hi:[0,1]
	v_pk_mul_f32 v[72:73], v[90:91], v[72:73] op_sel_hi:[0,1]
.LBB0_205:
	v_add_u32_e32 v82, 0x15000, v98
	v_cvt_pk_bf16_f32 v76, v76, v77
	v_cvt_pk_bf16_f32 v77, v78, v79
	v_cvt_pk_bf16_f32 v78, v72, v73
	v_cvt_pk_bf16_f32 v79, v74, v75
	v_add_lshl_u32 v72, v82, v152, 1
	s_and_b64 vcc, exec, s[8:9]
	global_store_dwordx4 v72, v[76:79], s[16:17]
	s_cbranch_vccnz .LBB0_207
	s_cmpk_lt_u32 s48, 0xf00
	s_cselect_b64 vcc, -1, 0
	v_cndmask_b32_e32 v80, 1.0, v151, vcc
	v_mov_b32_e32 v72, v216
	v_mov_b32_e32 v73, v217
	v_mov_b32_e32 v74, v218
	v_mov_b32_e32 v75, v219
	v_mov_b32_e32 v76, v220
	v_mov_b32_e32 v77, v221
	v_mov_b32_e32 v78, v222
	v_mov_b32_e32 v79, v223
	v_mov_b32_e32 v84, v73
	v_mov_b32_e32 v85, v75
	v_mov_b32_e32 v86, v77
	v_mov_b32_e32 v87, v79
	v_mov_b32_e32 v77, v78
	v_mov_b32_e32 v73, v74
	v_pk_mul_f32 v[74:75], v[66:67], v[84:85]
	v_pk_mul_f32 v[78:79], v[64:65], v[86:87]
	v_pk_mul_f32 v[84:85], v[70:71], v[84:85]
	v_pk_mul_f32 v[86:87], v[68:69], v[86:87]
	v_pk_fma_f32 v[68:69], v[68:69], v[76:77], v[78:79] neg_lo:[0,0,1] neg_hi:[0,0,1]
	v_pk_fma_f32 v[70:71], v[70:71], v[72:73], v[74:75] neg_lo:[0,0,1] neg_hi:[0,0,1]
	v_pk_fma_f32 v[64:65], v[64:65], v[76:77], v[86:87]
	v_pk_fma_f32 v[66:67], v[66:67], v[72:73], v[84:85]
	v_pk_mul_f32 v[70:71], v[80:81], v[70:71] op_sel_hi:[0,1]
	v_pk_mul_f32 v[68:69], v[80:81], v[68:69] op_sel_hi:[0,1]
	v_pk_mul_f32 v[66:67], v[80:81], v[66:67] op_sel_hi:[0,1]
	v_pk_mul_f32 v[64:65], v[80:81], v[64:65] op_sel_hi:[0,1]
.LBB0_207:
	v_cvt_pk_bf16_f32 v68, v68, v69
	v_cvt_pk_bf16_f32 v69, v70, v71
	v_cvt_pk_bf16_f32 v70, v64, v65
	v_cvt_pk_bf16_f32 v71, v66, v67
	v_add_lshl_u32 v64, v82, v120, 1
	global_store_dwordx4 v64, v[68:71], s[16:17]
	v_lshlrev_b64 v[64:65], 8, v[134:135]
	v_lshl_add_u64 v[64:65], v[64:65], 0, s[20:21]
	s_and_b64 vcc, exec, s[6:7]
	v_lshl_add_u64 v[64:65], v[128:129], 0, v[64:65]
	s_cbranch_vccnz .LBB0_209
	s_mov_b64 s[98:99], 0x9000
	v_lshl_add_u64 v[226:227], v[224:225], 0, s[98:99]
	global_load_dwordx4 v[200:203], v[226:227], off offset:16
	global_load_dwordx4 v[204:207], v[226:227], off
	s_cmpk_lt_u32 s48, 0xf00
	s_cselect_b64 vcc, -1, 0
	v_cndmask_b32_e32 v74, 1.0, v151, vcc
	s_waitcnt vmcnt(4)
	v_mov_b32_e32 v66, v192
	v_mov_b32_e32 v67, v193
	v_mov_b32_e32 v68, v194
	v_mov_b32_e32 v69, v195
	v_mov_b32_e32 v70, v196
	v_mov_b32_e32 v71, v197
	v_mov_b32_e32 v72, v198
	v_mov_b32_e32 v73, v199
	v_mov_b32_e32 v76, v67
	v_mov_b32_e32 v77, v69
	v_mov_b32_e32 v78, v71
	v_mov_b32_e32 v79, v73
	v_mov_b32_e32 v71, v72
	v_mov_b32_e32 v67, v68
	v_pk_mul_f32 v[68:69], v[58:59], v[76:77]
	v_pk_mul_f32 v[72:73], v[56:57], v[78:79]
	v_pk_mul_f32 v[76:77], v[62:63], v[76:77]
	v_pk_mul_f32 v[78:79], v[60:61], v[78:79]
	v_pk_fma_f32 v[60:61], v[60:61], v[70:71], v[72:73] neg_lo:[0,0,1] neg_hi:[0,0,1]
	v_pk_fma_f32 v[62:63], v[62:63], v[66:67], v[68:69] neg_lo:[0,0,1] neg_hi:[0,0,1]
	v_pk_fma_f32 v[56:57], v[56:57], v[70:71], v[78:79]
	v_pk_fma_f32 v[58:59], v[58:59], v[66:67], v[76:77]
	v_pk_mul_f32 v[62:63], v[74:75], v[62:63] op_sel_hi:[0,1]
	v_pk_mul_f32 v[60:61], v[74:75], v[60:61] op_sel_hi:[0,1]
	v_pk_mul_f32 v[58:59], v[74:75], v[58:59] op_sel_hi:[0,1]
	v_pk_mul_f32 v[56:57], v[74:75], v[56:57] op_sel_hi:[0,1]
.LBB0_209:
	v_add_u32_e32 v66, 0x69000, v82
	v_cvt_pk_bf16_f32 v60, v60, v61
	v_cvt_pk_bf16_f32 v61, v62, v63
	v_cvt_pk_bf16_f32 v62, v56, v57
	v_cvt_pk_bf16_f32 v63, v58, v59
	v_add_lshl_u32 v56, v66, v152, 1
	s_and_b64 vcc, exec, s[8:9]
	global_store_dwordx4 v56, v[60:63], s[16:17]
	s_cbranch_vccnz .LBB0_211
	s_cmpk_lt_u32 s48, 0xf00
	s_cselect_b64 vcc, -1, 0
	v_cndmask_b32_e32 v64, 1.0, v151, vcc
	v_mov_b32_e32 v56, v192
	v_mov_b32_e32 v57, v193
	v_mov_b32_e32 v58, v194
	v_mov_b32_e32 v59, v195
	v_mov_b32_e32 v60, v196
	v_mov_b32_e32 v61, v197
	v_mov_b32_e32 v62, v198
	v_mov_b32_e32 v63, v199
	v_mov_b32_e32 v68, v57
	v_mov_b32_e32 v69, v59
	v_mov_b32_e32 v70, v61
	v_mov_b32_e32 v71, v63
	v_mov_b32_e32 v61, v62
	v_mov_b32_e32 v57, v58
	v_pk_mul_f32 v[58:59], v[50:51], v[68:69]
	v_pk_mul_f32 v[62:63], v[48:49], v[70:71]
	v_pk_mul_f32 v[68:69], v[54:55], v[68:69]
	v_pk_mul_f32 v[70:71], v[52:53], v[70:71]
	v_pk_fma_f32 v[52:53], v[52:53], v[60:61], v[62:63] neg_lo:[0,0,1] neg_hi:[0,0,1]
	v_pk_fma_f32 v[54:55], v[54:55], v[56:57], v[58:59] neg_lo:[0,0,1] neg_hi:[0,0,1]
	v_pk_fma_f32 v[48:49], v[48:49], v[60:61], v[70:71]
	v_pk_fma_f32 v[50:51], v[50:51], v[56:57], v[68:69]
	v_pk_mul_f32 v[54:55], v[64:65], v[54:55] op_sel_hi:[0,1]
	v_pk_mul_f32 v[52:53], v[64:65], v[52:53] op_sel_hi:[0,1]
	v_pk_mul_f32 v[50:51], v[64:65], v[50:51] op_sel_hi:[0,1]
	v_pk_mul_f32 v[48:49], v[64:65], v[48:49] op_sel_hi:[0,1]
;     __device__ __forceinline__ void operator()(const f32x4 (&acc)[2][2][4][2], const Unit& u, int wr, int wc, int fr, int fq) const {
;     ...
;             for (int m = 0; m < 4; ++m) {
; #pragma unroll
;                 for (int bj = 0; bj < 2; ++bj) f(row0 + ai * HALF + m * 16, col0 + bj * HALF, acc[ai][bj][m][0], acc[ai][bj][m][1]);
.LBB0_211:
	v_cvt_pk_bf16_f32 v52, v52, v53
	v_cvt_pk_bf16_f32 v53, v54, v55
	v_cvt_pk_bf16_f32 v54, v48, v49
	v_cvt_pk_bf16_f32 v55, v50, v51
	v_add_lshl_u32 v48, v66, v120, 1
	global_store_dwordx4 v48, v[52:55], s[16:17]
	v_lshlrev_b64 v[48:49], 8, v[134:135]
	v_lshl_add_u64 v[48:49], v[48:49], 0, s[22:23]
	s_and_b64 vcc, exec, s[6:7]
	v_lshl_add_u64 v[48:49], v[128:129], 0, v[48:49]
	s_cbranch_vccnz .LBB0_213
	s_mov_b64 s[98:99], 0xa000
	v_lshl_add_u64 v[226:227], v[224:225], 0, s[98:99]
	global_load_dwordx4 v[208:211], v[226:227], off offset:16
	global_load_dwordx4 v[212:215], v[226:227], off
	s_cmpk_lt_u32 s48, 0xf00
	s_cselect_b64 vcc, -1, 0
	v_cndmask_b32_e32 v58, 1.0, v151, vcc
	s_waitcnt vmcnt(4)
	v_mov_b32_e32 v50, v200
	v_mov_b32_e32 v51, v201
	v_mov_b32_e32 v52, v202
	v_mov_b32_e32 v53, v203
	v_mov_b32_e32 v54, v204
	v_mov_b32_e32 v55, v205
	v_mov_b32_e32 v56, v206
	v_mov_b32_e32 v57, v207
	v_mov_b32_e32 v60, v51
	v_mov_b32_e32 v61, v53
	v_mov_b32_e32 v62, v55
	v_mov_b32_e32 v63, v57
	v_mov_b32_e32 v55, v56
	v_mov_b32_e32 v51, v52
	v_pk_mul_f32 v[52:53], v[42:43], v[60:61]
	v_pk_mul_f32 v[56:57], v[40:41], v[62:63]
	v_pk_mul_f32 v[60:61], v[46:47], v[60:61]
	v_pk_mul_f32 v[62:63], v[44:45], v[62:63]
	v_pk_fma_f32 v[44:45], v[44:45], v[54:55], v[56:57] neg_lo:[0,0,1] neg_hi:[0,0,1]
	v_pk_fma_f32 v[46:47], v[46:47], v[50:51], v[52:53] neg_lo:[0,0,1] neg_hi:[0,0,1]
	v_pk_fma_f32 v[40:41], v[40:41], v[54:55], v[62:63]
	v_pk_fma_f32 v[42:43], v[42:43], v[50:51], v[60:61]
	v_pk_mul_f32 v[46:47], v[58:59], v[46:47] op_sel_hi:[0,1]
	v_pk_mul_f32 v[44:45], v[58:59], v[44:45] op_sel_hi:[0,1]
	v_pk_mul_f32 v[42:43], v[58:59], v[42:43] op_sel_hi:[0,1]
	v_pk_mul_f32 v[40:41], v[58:59], v[40:41] op_sel_hi:[0,1]
.LBB0_213:
	v_add_u32_e32 v50, 0x15000, v66
	v_cvt_pk_bf16_f32 v44, v44, v45
	v_cvt_pk_bf16_f32 v45, v46, v47
	v_cvt_pk_bf16_f32 v46, v40, v41
	v_cvt_pk_bf16_f32 v47, v42, v43
	v_add_lshl_u32 v40, v50, v152, 1
	s_and_b64 vcc, exec, s[8:9]
	global_store_dwordx4 v40, v[44:47], s[16:17]
	s_cbranch_vccnz .LBB0_215
	s_cmpk_lt_u32 s48, 0xf00
	s_cselect_b64 vcc, -1, 0
	v_cndmask_b32_e32 v48, 1.0, v151, vcc
	v_mov_b32_e32 v40, v200
	v_mov_b32_e32 v41, v201
	v_mov_b32_e32 v42, v202
	v_mov_b32_e32 v43, v203
	v_mov_b32_e32 v44, v204
	v_mov_b32_e32 v45, v205
	v_mov_b32_e32 v46, v206
	v_mov_b32_e32 v47, v207
	v_mov_b32_e32 v52, v41
	v_mov_b32_e32 v53, v43
	v_mov_b32_e32 v54, v45
	v_mov_b32_e32 v55, v47
	v_mov_b32_e32 v45, v46
	v_mov_b32_e32 v41, v42
	v_pk_mul_f32 v[42:43], v[34:35], v[52:53]
	v_pk_mul_f32 v[46:47], v[32:33], v[54:55]
	v_pk_mul_f32 v[52:53], v[38:39], v[52:53]
	v_pk_mul_f32 v[54:55], v[36:37], v[54:55]
	v_pk_fma_f32 v[36:37], v[36:37], v[44:45], v[46:47] neg_lo:[0,0,1] neg_hi:[0,0,1]
	v_pk_fma_f32 v[38:39], v[38:39], v[40:41], v[42:43] neg_lo:[0,0,1] neg_hi:[0,0,1]
	v_pk_fma_f32 v[32:33], v[32:33], v[44:45], v[54:55]
	v_pk_fma_f32 v[34:35], v[34:35], v[40:41], v[52:53]
	v_pk_mul_f32 v[38:39], v[48:49], v[38:39] op_sel_hi:[0,1]
	v_pk_mul_f32 v[36:37], v[48:49], v[36:37] op_sel_hi:[0,1]
	v_pk_mul_f32 v[34:35], v[48:49], v[34:35] op_sel_hi:[0,1]
	v_pk_mul_f32 v[32:33], v[48:49], v[32:33] op_sel_hi:[0,1]
.LBB0_215:
	v_cvt_pk_bf16_f32 v36, v36, v37
	v_cvt_pk_bf16_f32 v37, v38, v39
	v_cvt_pk_bf16_f32 v38, v32, v33
	v_cvt_pk_bf16_f32 v39, v34, v35
	v_add_lshl_u32 v32, v50, v120, 1
	global_store_dwordx4 v32, v[36:39], s[16:17]
	v_lshlrev_b64 v[32:33], 8, v[134:135]
	v_lshl_add_u64 v[32:33], v[32:33], 0, s[36:37]
	s_and_b64 vcc, exec, s[6:7]
	v_lshl_add_u64 v[32:33], v[128:129], 0, v[32:33]
	s_cbranch_vccnz .LBB0_217
	s_mov_b64 s[98:99], 0xb000
	v_lshl_add_u64 v[226:227], v[224:225], 0, s[98:99]
	global_load_dwordx4 v[216:219], v[226:227], off offset:16
	global_load_dwordx4 v[220:223], v[226:227], off
	s_cmpk_lt_u32 s48, 0xf00
	s_cselect_b64 vcc, -1, 0
	v_cndmask_b32_e32 v42, 1.0, v151, vcc
	s_waitcnt vmcnt(4)
	v_mov_b32_e32 v34, v208
	v_mov_b32_e32 v35, v209
	v_mov_b32_e32 v36, v210
	v_mov_b32_e32 v37, v211
	v_mov_b32_e32 v38, v212
	v_mov_b32_e32 v39, v213
	v_mov_b32_e32 v40, v214
	v_mov_b32_e32 v41, v215
	v_mov_b32_e32 v44, v35
	v_mov_b32_e32 v45, v37
	v_mov_b32_e32 v46, v39
	v_mov_b32_e32 v47, v41
	v_mov_b32_e32 v39, v40
	v_mov_b32_e32 v35, v36
	v_pk_mul_f32 v[36:37], v[26:27], v[44:45]
	v_pk_mul_f32 v[40:41], v[24:25], v[46:47]
	v_pk_mul_f32 v[44:45], v[30:31], v[44:45]
	v_pk_mul_f32 v[46:47], v[28:29], v[46:47]
	v_pk_fma_f32 v[28:29], v[28:29], v[38:39], v[40:41] neg_lo:[0,0,1] neg_hi:[0,0,1]
	v_pk_fma_f32 v[30:31], v[30:31], v[34:35], v[36:37] neg_lo:[0,0,1] neg_hi:[0,0,1]
	v_pk_fma_f32 v[24:25], v[24:25], v[38:39], v[46:47]
	v_pk_fma_f32 v[26:27], v[26:27], v[34:35], v[44:45]
	v_pk_mul_f32 v[30:31], v[42:43], v[30:31] op_sel_hi:[0,1]
	v_pk_mul_f32 v[28:29], v[42:43], v[28:29] op_sel_hi:[0,1]
	v_pk_mul_f32 v[26:27], v[42:43], v[26:27] op_sel_hi:[0,1]
	v_pk_mul_f32 v[24:25], v[42:43], v[24:25] op_sel_hi:[0,1]
;     __device__ __forceinline__ void operator()(const f32x4 (&acc)[2][2][4][2], const Unit& u, int wr, int wc, int fr, int fq) const {
;     ...
;             for (int m = 0; m < 4; ++m) {
; #pragma unroll
;                 for (int bj = 0; bj < 2; ++bj) f(row0 + ai * HALF + m * 16, col0 + bj * HALF, acc[ai][bj][m][0], acc[ai][bj][m][1]);
.LBB0_217:
	v_add_u32_e32 v34, 0x15000, v50
	v_cvt_pk_bf16_f32 v28, v28, v29
	v_cvt_pk_bf16_f32 v29, v30, v31
	v_cvt_pk_bf16_f32 v30, v24, v25
	v_cvt_pk_bf16_f32 v31, v26, v27
	v_add_lshl_u32 v24, v34, v152, 1
	s_and_b64 vcc, exec, s[8:9]
	global_store_dwordx4 v24, v[28:31], s[16:17]
	s_cbranch_vccnz .LBB0_219
	s_cmpk_lt_u32 s48, 0xf00
	s_cselect_b64 vcc, -1, 0
	v_cndmask_b32_e32 v32, 1.0, v151, vcc
	v_mov_b32_e32 v24, v208
	v_mov_b32_e32 v25, v209
	v_mov_b32_e32 v26, v210
	v_mov_b32_e32 v27, v211
	v_mov_b32_e32 v28, v212
	v_mov_b32_e32 v29, v213
	v_mov_b32_e32 v30, v214
	v_mov_b32_e32 v31, v215
	v_mov_b32_e32 v36, v25
	v_mov_b32_e32 v37, v27
	v_mov_b32_e32 v38, v29
	v_mov_b32_e32 v39, v31
	v_mov_b32_e32 v29, v30
	v_mov_b32_e32 v25, v26
	v_pk_mul_f32 v[26:27], v[18:19], v[36:37]
	v_pk_mul_f32 v[30:31], v[16:17], v[38:39]
	v_pk_mul_f32 v[36:37], v[22:23], v[36:37]
	v_pk_mul_f32 v[38:39], v[20:21], v[38:39]
	v_pk_fma_f32 v[20:21], v[20:21], v[28:29], v[30:31] neg_lo:[0,0,1] neg_hi:[0,0,1]
	v_pk_fma_f32 v[22:23], v[22:23], v[24:25], v[26:27] neg_lo:[0,0,1] neg_hi:[0,0,1]
	v_pk_fma_f32 v[16:17], v[16:17], v[28:29], v[38:39]
	v_pk_fma_f32 v[18:19], v[18:19], v[24:25], v[36:37]
	v_pk_mul_f32 v[22:23], v[32:33], v[22:23] op_sel_hi:[0,1]
	v_pk_mul_f32 v[20:21], v[32:33], v[20:21] op_sel_hi:[0,1]
	v_pk_mul_f32 v[18:19], v[32:33], v[18:19] op_sel_hi:[0,1]
	v_pk_mul_f32 v[16:17], v[32:33], v[16:17] op_sel_hi:[0,1]
.LBB0_219:
	v_cvt_pk_bf16_f32 v20, v20, v21
	v_cvt_pk_bf16_f32 v21, v22, v23
	v_cvt_pk_bf16_f32 v22, v16, v17
	v_cvt_pk_bf16_f32 v23, v18, v19
	v_add_lshl_u32 v16, v34, v120, 1
	global_store_dwordx4 v16, v[20:23], s[16:17]
	v_lshlrev_b64 v[16:17], 8, v[134:135]
	v_lshl_add_u64 v[16:17], v[16:17], 0, s[38:39]
	s_and_b64 vcc, exec, s[6:7]
	v_lshl_add_u64 v[16:17], v[128:129], 0, v[16:17]
	s_cbranch_vccnz .LBB0_221
	s_cmpk_lt_u32 s48, 0xf00
	s_cselect_b64 vcc, -1, 0
	v_cndmask_b32_e32 v26, 1.0, v151, vcc
	s_waitcnt vmcnt(2)
	v_mov_b32_e32 v18, v216
	v_mov_b32_e32 v19, v217
	v_mov_b32_e32 v20, v218
	v_mov_b32_e32 v21, v219
	v_mov_b32_e32 v22, v220
	v_mov_b32_e32 v23, v221
	v_mov_b32_e32 v24, v222
	v_mov_b32_e32 v25, v223
	v_mov_b32_e32 v28, v19
	v_mov_b32_e32 v29, v21
	v_mov_b32_e32 v30, v23
	v_mov_b32_e32 v31, v25
	v_mov_b32_e32 v23, v24
	v_mov_b32_e32 v19, v20
	v_pk_mul_f32 v[20:21], v[10:11], v[28:29]
	v_pk_mul_f32 v[24:25], v[8:9], v[30:31]
	v_pk_mul_f32 v[28:29], v[14:15], v[28:29]
	v_pk_mul_f32 v[30:31], v[12:13], v[30:31]
	v_pk_fma_f32 v[12:13], v[12:13], v[22:23], v[24:25] neg_lo:[0,0,1] neg_hi:[0,0,1]
	v_pk_fma_f32 v[14:15], v[14:15], v[18:19], v[20:21] neg_lo:[0,0,1] neg_hi:[0,0,1]
	v_pk_fma_f32 v[8:9], v[8:9], v[22:23], v[30:31]
	v_pk_fma_f32 v[10:11], v[10:11], v[18:19], v[28:29]
	v_pk_mul_f32 v[14:15], v[26:27], v[14:15] op_sel_hi:[0,1]
	v_pk_mul_f32 v[12:13], v[26:27], v[12:13] op_sel_hi:[0,1]
	v_pk_mul_f32 v[10:11], v[26:27], v[10:11] op_sel_hi:[0,1]
	v_pk_mul_f32 v[8:9], v[26:27], v[8:9] op_sel_hi:[0,1]
.LBB0_221:
	v_add_u32_e32 v18, 0x15000, v34
	v_cvt_pk_bf16_f32 v12, v12, v13
	v_cvt_pk_bf16_f32 v13, v14, v15
	v_cvt_pk_bf16_f32 v14, v8, v9
	v_cvt_pk_bf16_f32 v15, v10, v11
	v_add_lshl_u32 v8, v18, v152, 1
	s_and_b64 vcc, exec, s[8:9]
	global_store_dwordx4 v8, v[12:15], s[16:17]
	s_cbranch_vccnz .LBB0_223
	s_cmpk_lt_u32 s48, 0xf00
	s_cselect_b64 vcc, -1, 0
	v_cndmask_b32_e32 v16, 1.0, v151, vcc
	v_mov_b32_e32 v8, v216
	v_mov_b32_e32 v9, v217
	v_mov_b32_e32 v10, v218
	v_mov_b32_e32 v11, v219
	v_mov_b32_e32 v12, v220
	v_mov_b32_e32 v13, v221
	v_mov_b32_e32 v14, v222
	v_mov_b32_e32 v15, v223
	v_mov_b32_e32 v20, v9
	v_mov_b32_e32 v21, v11
	v_mov_b32_e32 v22, v13
	v_mov_b32_e32 v23, v15
	v_mov_b32_e32 v13, v14
	v_mov_b32_e32 v9, v10
	v_pk_mul_f32 v[10:11], v[2:3], v[20:21]
	v_pk_mul_f32 v[14:15], v[0:1], v[22:23]
	v_pk_mul_f32 v[20:21], v[6:7], v[20:21]
	v_pk_mul_f32 v[22:23], v[4:5], v[22:23]
	v_pk_fma_f32 v[4:5], v[4:5], v[12:13], v[14:15] neg_lo:[0,0,1] neg_hi:[0,0,1]
	v_pk_fma_f32 v[6:7], v[6:7], v[8:9], v[10:11] neg_lo:[0,0,1] neg_hi:[0,0,1]
	v_pk_fma_f32 v[0:1], v[0:1], v[12:13], v[22:23]
	v_pk_fma_f32 v[2:3], v[2:3], v[8:9], v[20:21]
	v_pk_mul_f32 v[6:7], v[16:17], v[6:7] op_sel_hi:[0,1]
	v_pk_mul_f32 v[4:5], v[16:17], v[4:5] op_sel_hi:[0,1]
	v_pk_mul_f32 v[2:3], v[16:17], v[2:3] op_sel_hi:[0,1]
	v_pk_mul_f32 v[0:1], v[16:17], v[0:1] op_sel_hi:[0,1]
